# E44: attention second tile-half QK^T reads its K/Q LDS fragments one step ahead (double-buffered fragment registers, counted lgkmcnt)
# speedup vs baseline: 1.0048x; 1.0004x over previous
.LBB0_2195:
	v_cndmask_b32_e64 v188, v132, v188, s[6:7]
	v_mul_f32_e32 v128, 0xbdd53b94, v188
	v_fmamk_f32 v80, v80, 0x3dd53b94, v128
	v_fmamk_f32 v81, v81, 0x3dd53b94, v128
	v_fmamk_f32 v82, v82, 0x3dd53b94, v128
	v_fmamk_f32 v83, v83, 0x3dd53b94, v128
	v_fmamk_f32 v84, v84, 0x3dd53b94, v128
	v_fmamk_f32 v85, v85, 0x3dd53b94, v128
	v_fmamk_f32 v86, v86, 0x3dd53b94, v128
	v_fmamk_f32 v87, v87, 0x3dd53b94, v128
	v_fmamk_f32 v88, v88, 0x3dd53b94, v128
	v_fmamk_f32 v89, v89, 0x3dd53b94, v128
	v_fmamk_f32 v90, v90, 0x3dd53b94, v128
	v_fmamk_f32 v91, v91, 0x3dd53b94, v128
	v_fmamk_f32 v92, v92, 0x3dd53b94, v128
	v_fmamk_f32 v93, v93, 0x3dd53b94, v128
	v_fmamk_f32 v94, v94, 0x3dd53b94, v128
	v_fmamk_f32 v95, v95, 0x3dd53b94, v128
	v_fmamk_f32 v217, v68, 0x3dd53b94, v128
	v_fmamk_f32 v132, v71, 0x3dd53b94, v128
	v_fmamk_f32 v133, v72, 0x3dd53b94, v128
	v_fmamk_f32 v218, v77, 0x3dd53b94, v128
	v_fmamk_f32 v213, v64, 0x3dd53b94, v128
	v_fmamk_f32 v214, v65, 0x3dd53b94, v128
	v_fmamk_f32 v215, v66, 0x3dd53b94, v128
	v_fmamk_f32 v216, v67, 0x3dd53b94, v128
	v_fmamk_f32 v130, v69, 0x3dd53b94, v128
	v_fmamk_f32 v131, v70, 0x3dd53b94, v128
	v_fmamk_f32 v134, v73, 0x3dd53b94, v128
	v_fmamk_f32 v135, v74, 0x3dd53b94, v128
	v_fmamk_f32 v212, v75, 0x3dd53b94, v128
	v_fmamk_f32 v129, v76, 0x3dd53b94, v128
	v_exp_f32_e32 v125, v80
	v_exp_f32_e32 v127, v81
	v_exp_f32_e32 v123, v82
	v_exp_f32_e32 v126, v83
	v_exp_f32_e32 v122, v84
	v_exp_f32_e32 v124, v85
	v_exp_f32_e32 v120, v86
	v_exp_f32_e32 v121, v87
	v_exp_f32_e32 v117, v88
	v_exp_f32_e32 v119, v89
	v_exp_f32_e32 v116, v90
	v_exp_f32_e32 v118, v91
	v_exp_f32_e32 v113, v92
	v_exp_f32_e32 v115, v93
	v_exp_f32_e32 v112, v94
	v_exp_f32_e32 v114, v95
	v_fmamk_f32 v219, v78, 0x3dd53b94, v128
	v_fmac_f32_e32 v128, 0x3dd53b94, v79
	s_waitcnt lgkmcnt(0)
	s_barrier
	ds_read_b128 v[64:67], v156 offset:32768
	ds_read_b128 v[68:71], v156 offset:45056
	ds_read_b128 v[224:227], v169 offset:32768
	ds_read_b128 v[228:231], v169 offset:45056
	ds_read_b128 v[244:247], v168 offset:32768
	ds_read_b128 v[248:251], v168 offset:45056
	v_exp_f32_e32 v216, v216
	v_exp_f32_e32 v130, v130
	s_waitcnt lgkmcnt(5)
	v_mfma_f32_32x32x16_bf16 v[80:95], v[64:67], v[108:111], 0
	v_exp_f32_e32 v131, v131
	v_exp_f32_e32 v129, v129
	v_exp_f32_e32 v219, v219
	v_exp_f32_e32 v128, v128
	s_waitcnt lgkmcnt(4)
	v_mfma_f32_32x32x16_bf16 v[64:79], v[68:71], v[108:111], 0
	s_waitcnt lgkmcnt(2)
	v_mfma_f32_32x32x16_bf16 v[64:79], v[228:231], v[104:107], v[64:79]
	v_mfma_f32_32x32x16_bf16 v[80:95], v[224:227], v[104:107], v[80:95]
	ds_read_b128 v[224:227], v167 offset:32768
	ds_read_b128 v[228:231], v167 offset:45056
	s_waitcnt lgkmcnt(2)
	v_mfma_f32_32x32x16_bf16 v[64:79], v[248:251], v[100:103], v[64:79]
	v_mfma_f32_32x32x16_bf16 v[80:95], v[244:247], v[100:103], v[80:95]
	ds_read_b128 v[244:247], v165 offset:32768
	ds_read_b128 v[248:251], v165 offset:45056
	ds_read_b128 v[220:223], v139
	s_waitcnt lgkmcnt(3)
	v_mfma_f32_32x32x16_bf16 v[64:79], v[228:231], v[96:99], v[64:79]
	v_mfma_f32_32x32x16_bf16 v[80:95], v[224:227], v[96:99], v[80:95]
	ds_read_b128 v[224:227], v166 offset:32768
	ds_read_b128 v[228:231], v166 offset:45056
	ds_read_b128 v[232:235], v139 offset:1024
	s_waitcnt lgkmcnt(3)
	v_mfma_f32_32x32x16_bf16 v[64:79], v[248:251], v[220:223], v[64:79]
	v_mfma_f32_32x32x16_bf16 v[80:95], v[244:247], v[220:223], v[80:95]
	ds_read_b128 v[244:247], v158 offset:32768
	ds_read_b128 v[248:251], v158 offset:45056
	ds_read_b128 v[220:223], v139 offset:2048
	s_waitcnt lgkmcnt(3)
	v_mfma_f32_32x32x16_bf16 v[64:79], v[228:231], v[232:235], v[64:79]
	v_mfma_f32_32x32x16_bf16 v[80:95], v[224:227], v[232:235], v[80:95]
	ds_read_b128 v[224:227], v157 offset:32768
	ds_read_b128 v[228:231], v157 offset:45056
	ds_read_b128 v[232:235], v139 offset:3072
	s_waitcnt lgkmcnt(3)
	v_mfma_f32_32x32x16_bf16 v[64:79], v[248:251], v[220:223], v[64:79]
	v_mfma_f32_32x32x16_bf16 v[80:95], v[244:247], v[220:223], v[80:95]
	ds_read_b128 v[244:247], v154 offset:32768
	ds_read_b128 v[248:251], v154 offset:45056
	ds_read_b128 v[220:223], v139 offset:4096
	s_waitcnt lgkmcnt(3)
	v_mfma_f32_32x32x16_bf16 v[64:79], v[228:231], v[232:235], v[64:79]
	v_mfma_f32_32x32x16_bf16 v[80:95], v[224:227], v[232:235], v[80:95]
	ds_read_b128 v[224:227], v153 offset:32768
	ds_read_b128 v[228:231], v153 offset:45056
	ds_read_b128 v[232:235], v139 offset:5120
	s_waitcnt lgkmcnt(3)
	v_mfma_f32_32x32x16_bf16 v[64:79], v[248:251], v[220:223], v[64:79]
	v_mfma_f32_32x32x16_bf16 v[80:95], v[244:247], v[220:223], v[80:95]
	ds_read_b128 v[244:247], v180 offset:32768
	ds_read_b128 v[248:251], v180 offset:45056
	ds_read_b128 v[220:223], v139 offset:6144
	s_waitcnt lgkmcnt(3)
	v_mfma_f32_32x32x16_bf16 v[64:79], v[228:231], v[232:235], v[64:79]
	v_mfma_f32_32x32x16_bf16 v[80:95], v[224:227], v[232:235], v[80:95]
	ds_read_b128 v[224:227], v179 offset:32768
	ds_read_b128 v[228:231], v179 offset:45056
	ds_read_b128 v[232:235], v139 offset:7168
	s_waitcnt lgkmcnt(3)
	v_mfma_f32_32x32x16_bf16 v[64:79], v[248:251], v[220:223], v[64:79]
	v_mfma_f32_32x32x16_bf16 v[80:95], v[244:247], v[220:223], v[80:95]
	s_waitcnt lgkmcnt(0)
	v_mfma_f32_32x32x16_bf16 v[64:79], v[228:231], v[232:235], v[64:79]
	v_exp_f32_e32 v228, v132
	v_add_f32_e32 v132, 0, v125
	v_add_f32_e32 v132, v127, v132
	v_add_f32_e32 v132, v123, v132
	v_add_f32_e32 v132, v126, v132
	v_add_f32_e32 v132, v122, v132
	v_add_f32_e32 v132, v124, v132
	v_add_f32_e32 v132, v120, v132
	v_add_f32_e32 v132, v121, v132
	v_add_f32_e32 v132, v117, v132
	v_add_f32_e32 v132, v119, v132
	v_add_f32_e32 v132, v116, v132
	v_add_f32_e32 v132, v118, v132
	v_mfma_f32_32x32x16_bf16 v[80:95], v[224:227], v[232:235], v[80:95]
	v_exp_f32_e32 v224, v213
	v_add_f32_e32 v132, v113, v132
	v_exp_f32_e32 v225, v214
	v_add_f32_e32 v132, v115, v132
	v_exp_f32_e32 v226, v215
	v_add_f32_e32 v132, v112, v132
	v_add_f32_e32 v132, v114, v132
	v_exp_f32_e32 v227, v217
	v_add_f32_e32 v132, v224, v132
	v_add_f32_e32 v132, v225, v132
	v_add_f32_e32 v132, v226, v132
	v_add_f32_e32 v132, v216, v132
	v_exp_f32_e32 v229, v133
	v_add_f32_e32 v132, v227, v132
	v_exp_f32_e32 v230, v134
	v_add_f32_e32 v132, v130, v132
	v_exp_f32_e32 v231, v135
	v_add_f32_e32 v132, v131, v132
	v_exp_f32_e32 v232, v212
	v_add_f32_e32 v132, v228, v132
	v_add_f32_e32 v132, v229, v132
	v_exp_f32_e32 v233, v218
	v_add_f32_e32 v132, v230, v132
	v_add_f32_e32 v132, v231, v132
	v_add_f32_e32 v132, v232, v132
	v_add_f32_e32 v132, v129, v132
	v_add_f32_e32 v132, v233, v132
	v_add_f32_e32 v132, v219, v132
	v_add_f32_e32 v217, v128, v132
	v_mov_b32_e32 v218, v217
	v_cvt_pk_bf16_f32 v132, v125, v127
	v_cvt_pk_bf16_f32 v133, v123, v126
	v_cvt_pk_bf16_f32 v134, v122, v124
	v_cvt_pk_bf16_f32 v135, v120, v121
	s_nop 1
	v_permlane32_swap_b32_e32 v217, v218
	v_permlane32_swap_b32_e32 v132, v134
	v_permlane32_swap_b32_e32 v133, v135
	v_cvt_pk_bf16_f32 v212, v117, v119
	v_cvt_pk_bf16_f32 v213, v116, v118
	v_cvt_pk_bf16_f32 v214, v113, v115
	v_cvt_pk_bf16_f32 v215, v112, v114
	v_cvt_pk_bf16_f32 v224, v224, v225
	v_cvt_pk_bf16_f32 v225, v226, v216
	v_cvt_pk_bf16_f32 v226, v227, v130
	v_cvt_pk_bf16_f32 v227, v131, v228
	v_cvt_pk_bf16_f32 v228, v229, v230
	v_cvt_pk_bf16_f32 v229, v231, v232
	v_cvt_pk_bf16_f32 v230, v129, v233
	v_cvt_pk_bf16_f32 v231, v219, v128
	s_nop 0
	v_permlane32_swap_b32_e32 v212, v214
	v_permlane32_swap_b32_e32 v213, v215
	v_permlane32_swap_b32_e32 v224, v226
	v_permlane32_swap_b32_e32 v225, v227
	v_permlane32_swap_b32_e32 v228, v230
	v_permlane32_swap_b32_e32 v229, v231
	v_add_co_u32_e32 v112, vcc, s64, v146
	s_mov_b32 s6, 0xe000
	s_nop 0
	v_addc_co_u32_e32 v113, vcc, 0, v147, vcc
	v_add_co_u32_e32 v116, vcc, s6, v146
	s_mov_b32 s6, 0x12000
	s_nop 0
	v_addc_co_u32_e32 v117, vcc, 0, v147, vcc
	v_add_co_u32_e32 v128, vcc, s6, v148
	global_load_dwordx4 v[112:115], v[112:113], off
	s_nop 0
	global_load_dwordx4 v[116:119], v[116:117], off
	v_addc_co_u32_e32 v129, vcc, 0, v149, vcc
	global_load_dwordx4 v[120:123], v[128:129], off
	global_load_dwordx4 v[124:127], v[128:129], off offset:128
	s_nop 0
	global_load_dwordx4 v[128:131], v[128:129], off offset:256
	ds_read_b64_tr_b16 v[146:147], v150 offset:0
	ds_read_b64_tr_b16 v[148:149], v150 offset:0x800
	ds_read_b64_tr_b16 v[232:233], v150 offset:0x1000
	ds_read_b64_tr_b16 v[234:235], v150 offset:0x1800
	ds_read_b64_tr_b16 v[236:237], v150 offset:0x2000
	ds_read_b64_tr_b16 v[238:239], v150 offset:0x2800
	ds_read_b64_tr_b16 v[240:241], v150 offset:0x3000
	ds_read_b64_tr_b16 v[242:243], v150 offset:0x3800
	s_waitcnt lgkmcnt(0)
	s_nop 0
	v_mfma_f32_32x32x16_bf16 v[0:15], v[132:135], v[146:149], v[0:15]
	ds_read_b64_tr_b16 v[146:147], v150 offset:0x200
	ds_read_b64_tr_b16 v[148:149], v150 offset:0xa00
	v_mfma_f32_32x32x16_bf16 v[0:15], v[212:215], v[232:235], v[0:15]
	ds_read_b64_tr_b16 v[232:233], v150 offset:0x1200
	ds_read_b64_tr_b16 v[234:235], v150 offset:0x1a00
	v_mfma_f32_32x32x16_bf16 v[0:15], v[224:227], v[236:239], v[0:15]
	ds_read_b64_tr_b16 v[236:237], v150 offset:0x2200
	ds_read_b64_tr_b16 v[238:239], v150 offset:0x2a00
	v_mfma_f32_32x32x16_bf16 v[0:15], v[228:231], v[240:243], v[0:15]
	ds_read_b64_tr_b16 v[240:241], v150 offset:0x3200
	ds_read_b64_tr_b16 v[242:243], v150 offset:0x3a00
	s_waitcnt lgkmcnt(0)
	v_mfma_f32_32x32x16_bf16 v[48:63], v[132:135], v[146:149], v[48:63]
	ds_read_b64_tr_b16 v[146:147], v150 offset:0x400
	ds_read_b64_tr_b16 v[148:149], v150 offset:0xc00
	v_mfma_f32_32x32x16_bf16 v[48:63], v[212:215], v[232:235], v[48:63]
	ds_read_b64_tr_b16 v[232:233], v150 offset:0x1400
	ds_read_b64_tr_b16 v[234:235], v150 offset:0x1c00
	v_mfma_f32_32x32x16_bf16 v[48:63], v[224:227], v[236:239], v[48:63]
	ds_read_b64_tr_b16 v[236:237], v150 offset:0x2400
	ds_read_b64_tr_b16 v[238:239], v150 offset:0x2c00
	v_mfma_f32_32x32x16_bf16 v[48:63], v[228:231], v[240:243], v[48:63]
	ds_read_b64_tr_b16 v[240:241], v150 offset:0x3400
	ds_read_b64_tr_b16 v[242:243], v150 offset:0x3c00
	s_waitcnt lgkmcnt(0)
	v_mfma_f32_32x32x16_bf16 v[32:47], v[132:135], v[146:149], v[32:47]
	ds_read_b64_tr_b16 v[146:147], v150 offset:0x600
	ds_read_b64_tr_b16 v[148:149], v150 offset:0xe00
	v_mfma_f32_32x32x16_bf16 v[32:47], v[212:215], v[232:235], v[32:47]
	ds_read_b64_tr_b16 v[232:233], v150 offset:0x1600
	ds_read_b64_tr_b16 v[234:235], v150 offset:0x1e00
	v_mfma_f32_32x32x16_bf16 v[32:47], v[224:227], v[236:239], v[32:47]
	ds_read_b64_tr_b16 v[236:237], v150 offset:0x2600
	ds_read_b64_tr_b16 v[238:239], v150 offset:0x2e00
	v_mfma_f32_32x32x16_bf16 v[32:47], v[228:231], v[240:243], v[32:47]
	ds_read_b64_tr_b16 v[240:241], v150 offset:0x3600
	ds_read_b64_tr_b16 v[242:243], v150 offset:0x3e00
	s_waitcnt lgkmcnt(0)
	v_mfma_f32_32x32x16_bf16 v[16:31], v[132:135], v[146:149], v[16:31]
	v_max_f32_e32 v132, v81, v81
	v_max_f32_e32 v133, v80, v80
	v_max_f32_e32 v132, v133, v132
	v_max3_f32 v132, v132, v82, v83
	v_max3_f32 v132, v132, v84, v85
	v_max3_f32 v132, v132, v86, v87
	v_max3_f32 v132, v132, v88, v89
	v_max3_f32 v132, v132, v90, v91
	v_max3_f32 v132, v132, v92, v93
	v_mfma_f32_32x32x16_bf16 v[16:31], v[212:215], v[232:235], v[16:31]
	v_max3_f32 v132, v132, v94, v95
	v_max3_f32 v132, v132, v64, v65
	v_max3_f32 v132, v132, v66, v67
	v_max3_f32 v132, v132, v68, v69
	v_max3_f32 v132, v132, v70, v71
	v_max3_f32 v132, v132, v72, v73
	v_max3_f32 v132, v132, v74, v75
	v_max3_f32 v132, v132, v76, v77
	v_mfma_f32_32x32x16_bf16 v[16:31], v[224:227], v[236:239], v[16:31]
	v_max3_f32 v132, v132, v78, v79
	v_mov_b32_e32 v133, v132
	s_nop 1
	v_permlane32_swap_b32_e32 v132, v133
	v_max_f32_e32 v133, v133, v133
	v_max_f32_e32 v132, v132, v132
	v_max_f32_e32 v132, v132, v133
	v_sub_f32_e32 v133, v132, v188
	v_cmp_ge_f32_e32 vcc, s1, v133
	v_max_f32_e32 v133, v188, v188
	v_max_f32_e32 v133, v133, v132
	v_mfma_f32_32x32x16_bf16 v[16:31], v[228:231], v[240:243], v[16:31]
	v_sub_f32_e32 v132, v188, v133
	v_mul_f32_e32 v132, 0x3dd53b94, v132
	v_exp_f32_e32 v132, v132
	s_cmp_eq_u64 vcc, exec
	s_cselect_b64 s[6:7], -1, 0
	s_barrier
	s_waitcnt vmcnt(0)
	v_cndmask_b32_e64 v132, v132, 1.0, s[6:7]
	v_cmp_gt_f32_e32 vcc, 1.0, v132
	s_waitcnt vmcnt(4)
	ds_write_b128 v163, v[112:115] offset:16384
	s_waitcnt vmcnt(3)
	ds_write_b128 v164, v[116:119] offset:16384
	s_waitcnt vmcnt(2)
	ds_write_b128 v159, v[120:123] offset:57344
	s_waitcnt vmcnt(1)
	ds_write_b128 v159, v[124:127] offset:57472
	s_waitcnt vmcnt(0)
	ds_write_b128 v159, v[128:131] offset:57600
	s_cbranch_vccz .LBB0_2199
	s_and_saveexec_b64 s[10:11], s[4:5]
	ds_write_b32 v174, v132 offset:128
	s_or_b64 exec, exec, s[10:11]
	s_waitcnt lgkmcnt(0)
	v_add_u32_e32 v124, v137, v160
	ds_read_b128 v[112:115], v124 offset:224
	ds_read_b128 v[116:119], v124 offset:192
	ds_read_b128 v[120:123], v124 offset:160
	ds_read_b128 v[124:127], v124 offset:128
	s_waitcnt lgkmcnt(3)
	v_pk_mul_f32 v[12:13], v[12:13], v[112:113]
	s_waitcnt lgkmcnt(2)
	v_pk_mul_f32 v[8:9], v[8:9], v[116:117]
	s_waitcnt lgkmcnt(1)
	v_pk_mul_f32 v[4:5], v[4:5], v[120:121]
	v_pk_mul_f32 v[14:15], v[14:15], v[114:115]
	v_pk_mul_f32 v[10:11], v[10:11], v[118:119]
	v_pk_mul_f32 v[6:7], v[6:7], v[122:123]
	s_waitcnt lgkmcnt(0)
	v_pk_mul_f32 v[2:3], v[2:3], v[126:127]
	v_pk_mul_f32 v[0:1], v[0:1], v[124:125]
	v_pk_mul_f32 v[60:61], v[60:61], v[112:113]
	v_pk_mul_f32 v[56:57], v[56:57], v[116:117]
	v_pk_mul_f32 v[52:53], v[52:53], v[120:121]
	v_pk_mul_f32 v[62:63], v[62:63], v[114:115]
	v_pk_mul_f32 v[58:59], v[58:59], v[118:119]
	v_pk_mul_f32 v[54:55], v[54:55], v[122:123]
	v_pk_mul_f32 v[50:51], v[50:51], v[126:127]
	v_pk_mul_f32 v[48:49], v[48:49], v[124:125]
	v_pk_mul_f32 v[44:45], v[44:45], v[112:113]
	v_pk_mul_f32 v[40:41], v[40:41], v[116:117]
	v_pk_mul_f32 v[36:37], v[36:37], v[120:121]
	v_pk_mul_f32 v[46:47], v[46:47], v[114:115]
	v_pk_mul_f32 v[42:43], v[42:43], v[118:119]
	v_pk_mul_f32 v[38:39], v[38:39], v[122:123]
	v_pk_mul_f32 v[34:35], v[34:35], v[126:127]
	v_pk_mul_f32 v[32:33], v[32:33], v[124:125]
	v_pk_mul_f32 v[28:29], v[28:29], v[112:113]
	v_pk_mul_f32 v[24:25], v[24:25], v[116:117]
	v_pk_mul_f32 v[20:21], v[20:21], v[120:121]
	v_pk_mul_f32 v[30:31], v[30:31], v[114:115]
	v_pk_mul_f32 v[26:27], v[26:27], v[118:119]
	v_pk_mul_f32 v[22:23], v[22:23], v[122:123]
	v_pk_mul_f32 v[18:19], v[18:19], v[126:127]
	v_pk_mul_f32 v[16:17], v[16:17], v[124:125]

.LBB0_2201:
	v_mov_b32_e32 v220, 0
	v_mov_b32_e32 v221, 0
	v_mov_b32_e32 v222, 0
	v_mov_b32_e32 v223, 0
	ds_read_b128 v[64:67], v156 offset:57344
	ds_read_b128 v[68:71], v191 offset:12288
	v_exp_f32_e32 v116, v116
	v_exp_f32_e32 v117, v117
	v_exp_f32_e32 v114, v114
	s_waitcnt lgkmcnt(1)
	v_mfma_f32_32x32x16_bf16 v[80:95], v[64:67], v[108:111], 0
	v_exp_f32_e32 v115, v115
	v_exp_f32_e32 v118, v118
	v_exp_f32_e32 v119, v119
	v_exp_f32_e32 v113, v113
	s_waitcnt lgkmcnt(0)
	v_mfma_f32_32x32x16_bf16 v[64:79], v[68:71], v[108:111], 0
	ds_read_b128 v[108:111], v169 offset:57344
	ds_read_b128 v[142:145], v193 offset:12288
	s_waitcnt lgkmcnt(1)
	v_mfma_f32_32x32x16_bf16 v[80:95], v[108:111], v[104:107], v[80:95]
	s_waitcnt lgkmcnt(0)
	v_mfma_f32_32x32x16_bf16 v[64:79], v[142:145], v[104:107], v[64:79]
	ds_read_b128 v[104:107], v168 offset:57344
	ds_read_b128 v[108:111], v192 offset:12288
	s_waitcnt lgkmcnt(1)
	v_mfma_f32_32x32x16_bf16 v[80:95], v[104:107], v[100:103], v[80:95]
	s_waitcnt lgkmcnt(0)
	v_mfma_f32_32x32x16_bf16 v[64:79], v[108:111], v[100:103], v[64:79]
	ds_read_b128 v[100:103], v167 offset:57344
	ds_read_b128 v[104:107], v200 offset:12288
	v_exp_f32_e32 v108, v124
	v_exp_f32_e32 v109, v125
	v_exp_f32_e32 v110, v120
	v_exp_f32_e32 v111, v121
	v_exp_f32_e32 v120, v122
	v_exp_f32_e32 v121, v123
	s_waitcnt lgkmcnt(1)
	v_mfma_f32_32x32x16_bf16 v[80:95], v[100:103], v[96:99], v[80:95]
	v_exp_f32_e32 v122, v112
	s_waitcnt lgkmcnt(0)
	v_mfma_f32_32x32x16_bf16 v[64:79], v[104:107], v[96:99], v[64:79]
	ds_read_b128 v[96:99], v165 offset:57344
	ds_read_b128 v[100:103], v201 offset:12288
	ds_read_b128 v[104:107], v139
	s_waitcnt lgkmcnt(0)
	v_mfma_f32_32x32x16_bf16 v[80:95], v[96:99], v[104:107], v[80:95]
	v_mfma_f32_32x32x16_bf16 v[64:79], v[100:103], v[104:107], v[64:79]
	ds_read_b128 v[96:99], v166 offset:57344
	ds_read_b128 v[100:103], v204 offset:12288
	ds_read_b128 v[104:107], v139 offset:1024
	s_waitcnt lgkmcnt(0)
	v_mfma_f32_32x32x16_bf16 v[80:95], v[96:99], v[104:107], v[80:95]
	v_mfma_f32_32x32x16_bf16 v[64:79], v[100:103], v[104:107], v[64:79]
	ds_read_b128 v[96:99], v158 offset:57344
	ds_read_b128 v[100:103], v202 offset:12288
	ds_read_b128 v[104:107], v139 offset:2048
	s_waitcnt lgkmcnt(0)
	v_mfma_f32_32x32x16_bf16 v[80:95], v[96:99], v[104:107], v[80:95]
	v_mfma_f32_32x32x16_bf16 v[64:79], v[100:103], v[104:107], v[64:79]
	ds_read_b128 v[96:99], v157 offset:57344
	ds_read_b128 v[100:103], v203 offset:12288
	ds_read_b128 v[104:107], v139 offset:3072
	s_waitcnt lgkmcnt(0)
	v_mfma_f32_32x32x16_bf16 v[80:95], v[96:99], v[104:107], v[80:95]
	v_mfma_f32_32x32x16_bf16 v[64:79], v[100:103], v[104:107], v[64:79]
	ds_read_b128 v[96:99], v154 offset:57344
	ds_read_b128 v[100:103], v206 offset:12288
	ds_read_b128 v[104:107], v139 offset:4096
	s_waitcnt lgkmcnt(0)
	v_mfma_f32_32x32x16_bf16 v[80:95], v[96:99], v[104:107], v[80:95]
	v_mfma_f32_32x32x16_bf16 v[64:79], v[100:103], v[104:107], v[64:79]
	ds_read_b128 v[96:99], v153 offset:57344
	ds_read_b128 v[100:103], v205 offset:12288
	ds_read_b128 v[104:107], v139 offset:5120
	s_waitcnt lgkmcnt(0)
	v_mfma_f32_32x32x16_bf16 v[80:95], v[96:99], v[104:107], v[80:95]
	v_mfma_f32_32x32x16_bf16 v[64:79], v[100:103], v[104:107], v[64:79]
	ds_read_b128 v[96:99], v180 offset:57344
	ds_read_b128 v[100:103], v207 offset:12288
	ds_read_b128 v[104:107], v139 offset:6144
	s_waitcnt lgkmcnt(0)
	v_mfma_f32_32x32x16_bf16 v[80:95], v[96:99], v[104:107], v[80:95]
	v_mfma_f32_32x32x16_bf16 v[64:79], v[100:103], v[104:107], v[64:79]
	ds_read_b128 v[96:99], v179 offset:57344
	ds_read_b128 v[100:103], v208 offset:12288
	ds_read_b128 v[104:107], v139 offset:7168
	s_waitcnt lgkmcnt(0)
	v_mfma_f32_32x32x16_bf16 v[80:95], v[96:99], v[104:107], v[80:95]
	v_add_f32_e32 v96, 0, v133
	v_add_f32_e32 v96, v214, v96
	v_add_f32_e32 v96, v134, v96
	v_add_f32_e32 v96, v215, v96
	v_add_f32_e32 v96, v213, v96
	v_add_f32_e32 v96, v216, v96
	v_add_f32_e32 v96, v135, v96
	v_add_f32_e32 v96, v212, v96
	v_add_f32_e32 v96, v146, v96
	v_add_f32_e32 v96, v148, v96
	v_add_f32_e32 v96, v147, v96
	v_add_f32_e32 v96, v149, v96
	v_mfma_f32_32x32x16_bf16 v[64:79], v[100:103], v[104:107], v[64:79]
	v_exp_f32_e32 v106, v126
	v_add_f32_e32 v96, v128, v96
	v_exp_f32_e32 v107, v127
	v_add_f32_e32 v96, v130, v96
	v_add_f32_e32 v96, v129, v96
	v_add_f32_e32 v96, v131, v96
	v_add_f32_e32 v96, v106, v96
	v_add_f32_e32 v96, v107, v96
	v_add_f32_e32 v96, v108, v96
	v_add_f32_e32 v96, v109, v96
	v_add_f32_e32 v96, v110, v96
	v_add_f32_e32 v96, v111, v96
	v_add_f32_e32 v96, v116, v96
	v_add_f32_e32 v96, v117, v96
	v_add_f32_e32 v96, v114, v96
	v_add_f32_e32 v96, v115, v96
	v_add_f32_e32 v96, v120, v96
	v_add_f32_e32 v96, v121, v96
	v_add_f32_e32 v96, v118, v96
	v_add_f32_e32 v96, v119, v96
	v_add_f32_e32 v96, v122, v96
	v_add_f32_e32 v96, v113, v96
	v_mov_b32_e32 v97, v96
	v_cvt_pk_bf16_f32 v98, v133, v214
	v_cvt_pk_bf16_f32 v99, v134, v215
	v_cvt_pk_bf16_f32 v100, v213, v216
	v_cvt_pk_bf16_f32 v101, v135, v212
	s_nop 1
	v_permlane32_swap_b32_e32 v96, v97
	v_permlane32_swap_b32_e32 v98, v100
	v_permlane32_swap_b32_e32 v99, v101
	v_cvt_pk_bf16_f32 v102, v146, v148
	v_cvt_pk_bf16_f32 v103, v147, v149
	v_cvt_pk_bf16_f32 v104, v128, v130
	v_cvt_pk_bf16_f32 v105, v129, v131
	v_cvt_pk_bf16_f32 v106, v106, v107
	v_cvt_pk_bf16_f32 v107, v108, v109
	v_cvt_pk_bf16_f32 v108, v110, v111
	v_cvt_pk_bf16_f32 v109, v116, v117
	v_cvt_pk_bf16_f32 v110, v114, v115
	v_cvt_pk_bf16_f32 v111, v120, v121
	v_cvt_pk_bf16_f32 v112, v118, v119
	v_cvt_pk_bf16_f32 v113, v122, v113
	s_nop 0
	v_permlane32_swap_b32_e32 v102, v104
	v_permlane32_swap_b32_e32 v103, v105
	v_permlane32_swap_b32_e32 v106, v108
	v_permlane32_swap_b32_e32 v107, v109
	v_permlane32_swap_b32_e32 v110, v112
	v_permlane32_swap_b32_e32 v111, v113
	ds_read_b64_tr_b16 v[114:115], v152 offset:0
	ds_read_b64_tr_b16 v[116:117], v152 offset:0x800
	ds_read_b64_tr_b16 v[118:119], v152 offset:0x1000
	ds_read_b64_tr_b16 v[120:121], v152 offset:0x1800
	ds_read_b64_tr_b16 v[122:123], v152 offset:0x2000
	ds_read_b64_tr_b16 v[124:125], v152 offset:0x2800
	ds_read_b64_tr_b16 v[126:127], v152 offset:0x3000
	ds_read_b64_tr_b16 v[128:129], v152 offset:0x3800
	s_waitcnt lgkmcnt(0)
	s_nop 0
	v_mfma_f32_32x32x16_bf16 v[0:15], v[98:101], v[114:117], v[0:15]
	ds_read_b64_tr_b16 v[114:115], v152 offset:0x200
	ds_read_b64_tr_b16 v[116:117], v152 offset:0xa00
	v_mfma_f32_32x32x16_bf16 v[0:15], v[102:105], v[118:121], v[0:15]
	ds_read_b64_tr_b16 v[118:119], v152 offset:0x1200
	ds_read_b64_tr_b16 v[120:121], v152 offset:0x1a00
	v_mfma_f32_32x32x16_bf16 v[0:15], v[106:109], v[122:125], v[0:15]
	ds_read_b64_tr_b16 v[122:123], v152 offset:0x2200
	ds_read_b64_tr_b16 v[124:125], v152 offset:0x2a00
	v_mfma_f32_32x32x16_bf16 v[0:15], v[110:113], v[126:129], v[0:15]
	ds_read_b64_tr_b16 v[126:127], v152 offset:0x3200
	ds_read_b64_tr_b16 v[128:129], v152 offset:0x3a00
	s_waitcnt lgkmcnt(0)
	v_mfma_f32_32x32x16_bf16 v[48:63], v[98:101], v[114:117], v[48:63]
	ds_read_b64_tr_b16 v[114:115], v152 offset:0x400
	ds_read_b64_tr_b16 v[116:117], v152 offset:0xc00
	v_mfma_f32_32x32x16_bf16 v[48:63], v[102:105], v[118:121], v[48:63]
	ds_read_b64_tr_b16 v[118:119], v152 offset:0x1400
	ds_read_b64_tr_b16 v[120:121], v152 offset:0x1c00
	v_mfma_f32_32x32x16_bf16 v[48:63], v[106:109], v[122:125], v[48:63]
	ds_read_b64_tr_b16 v[122:123], v152 offset:0x2400
	ds_read_b64_tr_b16 v[124:125], v152 offset:0x2c00
	v_mfma_f32_32x32x16_bf16 v[48:63], v[110:113], v[126:129], v[48:63]
	ds_read_b64_tr_b16 v[126:127], v152 offset:0x3400
	ds_read_b64_tr_b16 v[128:129], v152 offset:0x3c00
	s_waitcnt lgkmcnt(0)
	v_mfma_f32_32x32x16_bf16 v[32:47], v[98:101], v[114:117], v[32:47]
	ds_read_b64_tr_b16 v[114:115], v152 offset:0x600
	ds_read_b64_tr_b16 v[116:117], v152 offset:0xe00
	v_mfma_f32_32x32x16_bf16 v[32:47], v[102:105], v[118:121], v[32:47]
	ds_read_b64_tr_b16 v[118:119], v152 offset:0x1600
	ds_read_b64_tr_b16 v[120:121], v152 offset:0x1e00
	v_mfma_f32_32x32x16_bf16 v[32:47], v[106:109], v[122:125], v[32:47]
	ds_read_b64_tr_b16 v[122:123], v152 offset:0x2600
	ds_read_b64_tr_b16 v[124:125], v152 offset:0x2e00
	v_mfma_f32_32x32x16_bf16 v[32:47], v[110:113], v[126:129], v[32:47]
	ds_read_b64_tr_b16 v[126:127], v152 offset:0x3600
	ds_read_b64_tr_b16 v[128:129], v152 offset:0x3e00
	s_waitcnt lgkmcnt(0)
	v_mfma_f32_32x32x16_bf16 v[16:31], v[98:101], v[114:117], v[16:31]
	v_max_f32_e32 v98, v81, v81
	v_max_f32_e32 v99, v80, v80
	v_max_f32_e32 v98, v99, v98
	v_max3_f32 v98, v98, v82, v83
	v_max3_f32 v98, v98, v84, v85
	v_max3_f32 v98, v98, v86, v87
	v_max3_f32 v98, v98, v88, v89
	v_max3_f32 v98, v98, v90, v91
	v_max3_f32 v98, v98, v92, v93
	v_mfma_f32_32x32x16_bf16 v[16:31], v[102:105], v[118:121], v[16:31]
	v_max3_f32 v98, v98, v94, v95
	v_max3_f32 v98, v98, v64, v65
	v_max3_f32 v98, v98, v66, v67
	v_max3_f32 v98, v98, v68, v69
	v_max3_f32 v98, v98, v70, v71
	v_max3_f32 v98, v98, v72, v73
	v_max3_f32 v98, v98, v74, v75
	v_max3_f32 v98, v98, v76, v77
	v_mfma_f32_32x32x16_bf16 v[16:31], v[106:109], v[122:125], v[16:31]
	v_max3_f32 v98, v98, v78, v79
	v_mov_b32_e32 v99, v98
	s_nop 1
	v_permlane32_swap_b32_e32 v98, v99
	v_max_f32_e32 v99, v99, v99
	v_max_f32_e32 v98, v98, v98
	v_max_f32_e32 v98, v98, v99
	v_sub_f32_e32 v99, v98, v188
	v_cmp_ge_f32_e32 vcc, s1, v99
	v_max_f32_e32 v99, v188, v188
	v_max_f32_e32 v99, v99, v98
	v_mfma_f32_32x32x16_bf16 v[16:31], v[110:113], v[126:129], v[16:31]
	v_sub_f32_e32 v98, v188, v99
	v_mul_f32_e32 v98, 0x3dd53b94, v98
	v_exp_f32_e32 v98, v98
	s_cmp_eq_u64 vcc, exec
	s_cselect_b64 s[6:7], -1, 0
	v_cndmask_b32_e64 v98, v98, 1.0, s[6:7]
	v_cmp_gt_f32_e32 vcc, 1.0, v98
	s_barrier
	s_cbranch_vccz .LBB0_2205
	s_and_saveexec_b64 s[10:11], s[4:5]
	ds_write_b32 v174, v98 offset:128
	s_or_b64 exec, exec, s[10:11]
	s_waitcnt lgkmcnt(0)
	v_add_u32_e32 v112, v137, v160
	ds_read_b128 v[100:103], v112 offset:224
	ds_read_b128 v[104:107], v112 offset:192
	ds_read_b128 v[108:111], v112 offset:160
	ds_read_b128 v[112:115], v112 offset:128
	s_waitcnt lgkmcnt(3)
	v_pk_mul_f32 v[12:13], v[12:13], v[100:101]
	s_waitcnt lgkmcnt(2)
	v_pk_mul_f32 v[8:9], v[8:9], v[104:105]
	s_waitcnt lgkmcnt(1)
	v_pk_mul_f32 v[4:5], v[4:5], v[108:109]
	v_pk_mul_f32 v[14:15], v[14:15], v[102:103]
	v_pk_mul_f32 v[10:11], v[10:11], v[106:107]
	v_pk_mul_f32 v[6:7], v[6:7], v[110:111]
	s_waitcnt lgkmcnt(0)
	v_pk_mul_f32 v[2:3], v[2:3], v[114:115]
	v_pk_mul_f32 v[0:1], v[0:1], v[112:113]
	v_pk_mul_f32 v[60:61], v[60:61], v[100:101]
	v_pk_mul_f32 v[56:57], v[56:57], v[104:105]
	v_pk_mul_f32 v[52:53], v[52:53], v[108:109]
	v_pk_mul_f32 v[62:63], v[62:63], v[102:103]
	v_pk_mul_f32 v[58:59], v[58:59], v[106:107]
	v_pk_mul_f32 v[54:55], v[54:55], v[110:111]
	v_pk_mul_f32 v[50:51], v[50:51], v[114:115]
	v_pk_mul_f32 v[48:49], v[48:49], v[112:113]
	v_pk_mul_f32 v[44:45], v[44:45], v[100:101]
	v_pk_mul_f32 v[40:41], v[40:41], v[104:105]
	v_pk_mul_f32 v[36:37], v[36:37], v[108:109]
	v_pk_mul_f32 v[46:47], v[46:47], v[102:103]
	v_pk_mul_f32 v[42:43], v[42:43], v[106:107]
	v_pk_mul_f32 v[38:39], v[38:39], v[110:111]
	v_pk_mul_f32 v[34:35], v[34:35], v[114:115]
	v_pk_mul_f32 v[32:33], v[32:33], v[112:113]
	v_pk_mul_f32 v[28:29], v[28:29], v[100:101]
	v_pk_mul_f32 v[24:25], v[24:25], v[104:105]
	v_pk_mul_f32 v[20:21], v[20:21], v[108:109]
	v_pk_mul_f32 v[30:31], v[30:31], v[102:103]
	v_pk_mul_f32 v[26:27], v[26:27], v[106:107]
	v_pk_mul_f32 v[22:23], v[22:23], v[110:111]
	v_pk_mul_f32 v[18:19], v[18:19], v[114:115]
	v_pk_mul_f32 v[16:17], v[16:17], v[112:113]
